# adds: P4 sample-row alpha items reassigned from WGs 0-7 to even (short-item) WGs 0,2,..,14
# speedup vs baseline: 1.0264x; 1.0016x over previous
.LBB0_817:
	s_add_u32 s0, s40, 0xdad6000
	s_addc_u32 s1, s41, 0
	s_add_u32 s8, s40, 0x10c56000
	s_addc_u32 s9, s41, 0
	v_mov_b32_e32 v189, v107
	v_mov_b32_e32 v143, v107
	v_mov_b32_e32 v147, v107
	v_mov_b32_e32 v151, v107
	v_mov_b32_e32 v155, v107
	v_mov_b32_e32 v159, v107
	v_mov_b32_e32 v163, v107
	v_mov_b32_e32 v167, v107
	v_mov_b32_e32 v171, v107
	v_mov_b32_e32 v175, v107
	v_mov_b32_e32 v179, v107
	v_mov_b32_e32 v183, v107
	v_mov_b32_e32 v187, v107
	v_lshl_add_u64 v[2:3], s[8:9], 0, v[188:189]
	v_or_b32_e32 v48, s44, v104
	v_lshl_add_u64 v[44:45], s[0:1], 0, v[142:143]
	v_lshl_add_u64 v[40:41], s[0:1], 0, v[146:147]
	v_lshl_add_u64 v[36:37], s[0:1], 0, v[150:151]
	v_lshl_add_u64 v[32:33], s[0:1], 0, v[154:155]
	v_lshl_add_u64 v[28:29], s[0:1], 0, v[158:159]
	v_lshl_add_u64 v[24:25], s[0:1], 0, v[162:163]
	v_lshl_add_u64 v[20:21], s[0:1], 0, v[166:167]
	v_lshl_add_u64 v[16:17], s[0:1], 0, v[170:171]
	v_lshl_add_u64 v[12:13], s[0:1], 0, v[174:175]
	v_lshl_add_u64 v[8:9], s[0:1], 0, v[178:179]
	v_lshl_add_u64 v[4:5], s[0:1], 0, v[182:183]
	v_lshl_add_u64 v[0:1], s[0:1], 0, v[186:187]
	v_mad_u64_u32 v[2:3], s[0:1], v48, 48, v[2:3]
	s_mul_i32 s0, s45, 48
	s_nop 0
	v_add_u32_e32 v3, s0, v3
	global_load_dword v50, v[2:3], off
	global_load_dword v51, v[2:3], off offset:16
	global_load_dword v52, v[2:3], off offset:32
	v_mov_b32_e32 v145, v107
	v_mov_b32_e32 v149, v107
	v_mov_b32_e32 v153, v107
	v_mov_b32_e32 v157, v107
	v_mov_b32_e32 v161, v107
	v_mov_b32_e32 v165, v107
	v_mov_b32_e32 v169, v107
	v_mov_b32_e32 v173, v107
	v_mov_b32_e32 v177, v107
	v_mov_b32_e32 v181, v107
	v_mov_b32_e32 v185, v107
	v_lshl_add_u64 v[46:47], s[8:9], 0, v[144:145]
	v_lshl_add_u64 v[42:43], s[8:9], 0, v[148:149]
	v_lshl_add_u64 v[38:39], s[8:9], 0, v[152:153]
	v_lshl_add_u64 v[34:35], s[8:9], 0, v[156:157]
	v_lshl_add_u64 v[30:31], s[8:9], 0, v[160:161]
	v_lshl_add_u64 v[26:27], s[8:9], 0, v[164:165]
	v_lshl_add_u64 v[22:23], s[8:9], 0, v[168:169]
	v_lshl_add_u64 v[18:19], s[8:9], 0, v[172:173]
	v_lshl_add_u64 v[14:15], s[8:9], 0, v[176:177]
	v_lshl_add_u64 v[10:11], s[8:9], 0, v[180:181]
	v_lshl_add_u64 v[6:7], s[8:9], 0, v[184:185]
	v_mad_u64_u32 v[48:49], s[8:9], v48, s3, v[0:1]
	v_readlane_b32 s8, v254, 13
	v_readlane_b32 s9, v254, 14
	s_mul_i32 s1, s45, 0xc00
	v_add_u32_e32 v49, s1, v49
	global_load_dwordx4 v[0:3], v[48:49], off
	v_lshl_add_u64 v[78:79], s[44:45], 0, v[120:121]
	v_lshl_add_u64 v[94:95], s[44:45], 0, v[128:129]
	s_add_i32 s49, s49, s96
	s_cmpk_eq_i32 s96, 0x100
	s_cbranch_scc0 .Lp4_keep
	s_cmpk_lt_i32 s49, 0x100
	s_cbranch_scc1 .Lp4_keep
	s_cmpk_gt_i32 s49, 0x1ff
	s_cbranch_scc1 .Lp4_exit
	s_bitcmp1_b32 s97, 0
	s_cbranch_scc1 .Lp4_exit
	s_cmpk_gt_i32 s97, 15
	s_cbranch_scc1 .Lp4_exit
	s_lshr_b32 s49, s97, 1
	s_addk_i32 s49, 0x100
	s_branch .Lp4_keep
.Lp4_exit:
	s_movk_i32 s49, 0x108
.Lp4_keep:
	s_waitcnt vmcnt(0)
	v_max3_f32 v53, v50, v51, v52
	v_sub_f32_e32 v51, v51, v53
	v_sub_f32_e32 v52, v52, v53
	v_sub_f32_e32 v50, v50, v53
	v_mul_f32_e32 v51, 0x3fb8aa3b, v51
	v_mul_f32_e32 v52, 0x3fb8aa3b, v52
	v_mul_f32_e32 v50, 0x3fb8aa3b, v50
	v_exp_f32_e32 v51, v51
	v_exp_f32_e32 v52, v52
	v_exp_f32_e32 v50, v50
	v_cndmask_b32_e64 v53, v52, v51, s[8:9]
	v_cndmask_b32_e64 v53, v53, v50, s[12:13]
	v_add_f32_e32 v50, v50, v51
	v_add_f32_e32 v50, v52, v50
	v_div_scale_f32 v51, s[8:9], v50, v50, v53
	v_rcp_f32_e32 v52, v51
	v_lshlrev_b32_e32 v96, 16, v0
	v_fma_f32 v54, -v51, v52, 1.0
	v_fmac_f32_e32 v52, v54, v52
	v_div_scale_f32 v54, vcc, v53, v50, v53
	v_mul_f32_e32 v55, v54, v52
	v_fma_f32 v56, -v51, v55, v54
	v_fmac_f32_e32 v55, v56, v52
	v_fma_f32 v51, -v51, v55, v54
	v_div_fmas_f32 v51, v51, v52, v55
	v_div_fixup_f32 v50, v51, v50, v53
	v_or_b32_e32 v51, s44, v108
	v_mad_u64_u32 v[6:7], s[8:9], v51, 48, v[6:7]
	v_add_u32_e32 v7, s0, v7
	global_load_dword v54, v[6:7], off
	global_load_dword v55, v[6:7], off offset:16
	global_load_dword v56, v[6:7], off offset:32
	v_mad_u64_u32 v[52:53], s[8:9], v51, s3, v[4:5]
	v_readlane_b32 s8, v254, 11
	v_readlane_b32 s9, v254, 12
	v_add_u32_e32 v53, s1, v53
	global_load_dwordx4 v[4:7], v[52:53], off
	v_and_b32_e32 v97, 0xffff0000, v0
	s_waitcnt vmcnt(1)
	v_max3_f32 v51, v54, v55, v56
	v_sub_f32_e32 v54, v54, v51
	v_sub_f32_e32 v55, v55, v51
	v_sub_f32_e32 v51, v56, v51
	v_mul_f32_e32 v55, 0x3fb8aa3b, v55
	v_mul_f32_e32 v51, 0x3fb8aa3b, v51
	v_exp_f32_e32 v55, v55
	v_exp_f32_e32 v51, v51
	v_mul_f32_e32 v54, 0x3fb8aa3b, v54
	v_exp_f32_e32 v54, v54
	v_cndmask_b32_e64 v56, v51, v55, s[8:9]
	v_readlane_b32 s8, v254, 17
	v_readlane_b32 s9, v254, 18
	s_nop 1
	v_cndmask_b32_e64 v56, v56, v54, s[8:9]
	v_add_f32_e32 v54, v54, v55
	v_add_f32_e32 v51, v51, v54
	v_div_scale_f32 v54, s[8:9], v51, v51, v56
	v_rcp_f32_e32 v55, v54
	s_nop 0
	v_fma_f32 v57, -v54, v55, 1.0
	v_fmac_f32_e32 v55, v57, v55
	v_div_scale_f32 v57, vcc, v56, v51, v56
	v_mul_f32_e32 v58, v57, v55
	v_fma_f32 v59, -v54, v58, v57
	v_fmac_f32_e32 v58, v59, v55
	v_fma_f32 v54, -v54, v58, v57
	v_div_fmas_f32 v54, v54, v55, v58
	v_div_fixup_f32 v54, v54, v51, v56
	v_or_b32_e32 v51, s44, v110
	v_mad_u64_u32 v[10:11], s[8:9], v51, 48, v[10:11]
	v_add_u32_e32 v11, s0, v11
	global_load_dword v55, v[10:11], off
	global_load_dword v58, v[10:11], off offset:16
	global_load_dword v59, v[10:11], off offset:32
	v_mad_u64_u32 v[56:57], s[8:9], v51, s3, v[8:9]
	v_readlane_b32 s8, v254, 21
	v_readlane_b32 s9, v254, 22
	v_add_u32_e32 v57, s1, v57
	global_load_dwordx4 v[8:11], v[56:57], off
	s_waitcnt vmcnt(1)
	v_max3_f32 v51, v55, v58, v59
	v_sub_f32_e32 v55, v55, v51
	v_sub_f32_e32 v58, v58, v51
	v_sub_f32_e32 v51, v59, v51
	v_mul_f32_e32 v58, 0x3fb8aa3b, v58
	v_mul_f32_e32 v51, 0x3fb8aa3b, v51
	v_exp_f32_e32 v58, v58
	v_exp_f32_e32 v51, v51
	v_mul_f32_e32 v55, 0x3fb8aa3b, v55
	v_exp_f32_e32 v55, v55
	v_cndmask_b32_e64 v59, v51, v58, s[8:9]
	v_readlane_b32 s8, v254, 19
	v_readlane_b32 s9, v254, 20
	s_nop 1
	v_cndmask_b32_e64 v59, v59, v55, s[8:9]
	v_add_f32_e32 v55, v55, v58
	v_add_f32_e32 v51, v51, v55
	v_div_scale_f32 v55, s[8:9], v51, v51, v59
	v_rcp_f32_e32 v58, v55
	s_nop 0
	v_fma_f32 v60, -v55, v58, 1.0
	v_fmac_f32_e32 v58, v60, v58
	v_div_scale_f32 v60, vcc, v59, v51, v59
	v_mul_f32_e32 v61, v60, v58
	v_fma_f32 v62, -v55, v61, v60
	v_fmac_f32_e32 v61, v62, v58
	v_fma_f32 v55, -v55, v61, v60
	v_div_fmas_f32 v55, v55, v58, v61
	v_div_fixup_f32 v58, v55, v51, v59
	v_or_b32_e32 v51, s44, v112
	v_mad_u64_u32 v[14:15], s[8:9], v51, 48, v[14:15]
	v_add_u32_e32 v15, s0, v15
	global_load_dword v55, v[14:15], off
	global_load_dword v59, v[14:15], off offset:16
	global_load_dword v62, v[14:15], off offset:32
	v_mad_u64_u32 v[60:61], s[8:9], v51, s3, v[12:13]
	v_readlane_b32 s8, v254, 27
	v_readlane_b32 s9, v254, 28
	v_add_u32_e32 v61, s1, v61
	global_load_dwordx4 v[12:15], v[60:61], off
	s_waitcnt vmcnt(1)
	v_max3_f32 v51, v55, v59, v62
	v_sub_f32_e32 v55, v55, v51
	v_sub_f32_e32 v59, v59, v51
	v_sub_f32_e32 v51, v62, v51
	v_mul_f32_e32 v59, 0x3fb8aa3b, v59
	v_mul_f32_e32 v51, 0x3fb8aa3b, v51
	v_exp_f32_e32 v59, v59
	v_exp_f32_e32 v51, v51
	v_mul_f32_e32 v55, 0x3fb8aa3b, v55
	v_exp_f32_e32 v55, v55
	v_cndmask_b32_e64 v62, v51, v59, s[8:9]
	v_readlane_b32 s8, v254, 23
	v_readlane_b32 s9, v254, 24
	s_nop 1
	v_cndmask_b32_e64 v62, v62, v55, s[8:9]
	v_add_f32_e32 v55, v55, v59
	v_add_f32_e32 v51, v51, v55
	v_div_scale_f32 v55, s[8:9], v51, v51, v62
	v_rcp_f32_e32 v59, v55
	s_nop 0
	v_fma_f32 v63, -v55, v59, 1.0
	v_fmac_f32_e32 v59, v63, v59
	v_div_scale_f32 v63, vcc, v62, v51, v62
	v_mul_f32_e32 v64, v63, v59
	v_fma_f32 v65, -v55, v64, v63
	v_fmac_f32_e32 v64, v65, v59
	v_fma_f32 v55, -v55, v64, v63
	v_div_fmas_f32 v55, v55, v59, v64
	v_div_fixup_f32 v62, v55, v51, v62
	v_or_b32_e32 v51, s44, v114
	v_mad_u64_u32 v[18:19], s[8:9], v51, 48, v[18:19]
	v_add_u32_e32 v19, s0, v19
	global_load_dword v55, v[18:19], off
	global_load_dword v59, v[18:19], off offset:16
	global_load_dword v63, v[18:19], off offset:32
	v_mad_u64_u32 v[64:65], s[8:9], v51, s3, v[16:17]
	v_readlane_b32 s8, v254, 9
	v_readlane_b32 s9, v254, 10
	v_add_u32_e32 v65, s1, v65
	global_load_dwordx4 v[16:19], v[64:65], off
	s_waitcnt vmcnt(1)
	v_max3_f32 v51, v55, v59, v63
	v_sub_f32_e32 v55, v55, v51
	v_sub_f32_e32 v59, v59, v51
	v_sub_f32_e32 v51, v63, v51
	v_mul_f32_e32 v59, 0x3fb8aa3b, v59
	v_mul_f32_e32 v51, 0x3fb8aa3b, v51
	v_exp_f32_e32 v59, v59
	v_exp_f32_e32 v51, v51
	v_mul_f32_e32 v55, 0x3fb8aa3b, v55
	v_exp_f32_e32 v55, v55
	v_cndmask_b32_e64 v63, v51, v59, s[8:9]
	v_readlane_b32 s8, v254, 25
	v_readlane_b32 s9, v254, 26
	s_nop 1
	v_cndmask_b32_e64 v63, v63, v55, s[8:9]
	v_add_f32_e32 v55, v55, v59
	v_add_f32_e32 v51, v51, v55
	v_div_scale_f32 v55, s[8:9], v51, v51, v63
	v_rcp_f32_e32 v59, v55
	s_nop 0
	v_fma_f32 v66, -v55, v59, 1.0
	v_fmac_f32_e32 v59, v66, v59
	v_div_scale_f32 v66, vcc, v63, v51, v63
	v_mul_f32_e32 v67, v66, v59
	v_fma_f32 v68, -v55, v67, v66
	v_fmac_f32_e32 v67, v68, v59
	v_fma_f32 v55, -v55, v67, v66
	v_div_fmas_f32 v55, v55, v59, v67
	v_div_fixup_f32 v66, v55, v51, v63
	v_or_b32_e32 v51, s44, v116
	v_mad_u64_u32 v[22:23], s[8:9], v51, 48, v[22:23]
	v_add_u32_e32 v23, s0, v23
	global_load_dword v55, v[22:23], off
	global_load_dword v59, v[22:23], off offset:16
	global_load_dword v63, v[22:23], off offset:32
	v_mad_u64_u32 v[68:69], s[8:9], v51, s3, v[20:21]
	v_readlane_b32 s8, v254, 47
	v_readlane_b32 s9, v254, 48
	v_add_u32_e32 v69, s1, v69
	global_load_dwordx4 v[20:23], v[68:69], off
	s_waitcnt vmcnt(1)
	v_max3_f32 v51, v55, v59, v63
	v_sub_f32_e32 v55, v55, v51
	v_sub_f32_e32 v59, v59, v51
	v_sub_f32_e32 v51, v63, v51
	v_mul_f32_e32 v59, 0x3fb8aa3b, v59
	v_mul_f32_e32 v51, 0x3fb8aa3b, v51
	v_exp_f32_e32 v59, v59
	v_exp_f32_e32 v51, v51
	v_mul_f32_e32 v55, 0x3fb8aa3b, v55
	v_exp_f32_e32 v55, v55
	v_cndmask_b32_e64 v63, v51, v59, s[8:9]
	v_readlane_b32 s8, v254, 45
	v_readlane_b32 s9, v254, 46
	s_nop 1
	v_cndmask_b32_e64 v63, v63, v55, s[8:9]
	v_add_f32_e32 v55, v55, v59
	v_add_f32_e32 v51, v51, v55
	v_div_scale_f32 v55, s[8:9], v51, v51, v63
	v_rcp_f32_e32 v59, v55
	s_nop 0
	v_fma_f32 v67, -v55, v59, 1.0
	v_fmac_f32_e32 v59, v67, v59
	v_div_scale_f32 v67, vcc, v63, v51, v63
	v_mul_f32_e32 v70, v67, v59
	v_fma_f32 v71, -v55, v70, v67
	v_fmac_f32_e32 v70, v71, v59
	v_fma_f32 v55, -v55, v70, v67
	v_div_fmas_f32 v55, v55, v59, v70
	v_div_fixup_f32 v70, v55, v51, v63
	v_or_b32_e32 v51, s44, v118
	v_mad_u64_u32 v[26:27], s[8:9], v51, 48, v[26:27]
	v_add_u32_e32 v27, s0, v27
	global_load_dword v55, v[26:27], off
	global_load_dword v59, v[26:27], off offset:16
	global_load_dword v63, v[26:27], off offset:32
	v_mad_u64_u32 v[72:73], s[8:9], v51, s3, v[24:25]
	v_readlane_b32 s8, v254, 31
	v_readlane_b32 s9, v254, 32
	v_add_u32_e32 v73, s1, v73
	global_load_dwordx4 v[24:27], v[72:73], off
	s_waitcnt vmcnt(1)
	v_max3_f32 v51, v55, v59, v63
	v_sub_f32_e32 v55, v55, v51
	v_sub_f32_e32 v59, v59, v51
	v_sub_f32_e32 v51, v63, v51
	v_mul_f32_e32 v59, 0x3fb8aa3b, v59
	v_mul_f32_e32 v51, 0x3fb8aa3b, v51
	v_exp_f32_e32 v59, v59
	v_exp_f32_e32 v51, v51
	v_mul_f32_e32 v55, 0x3fb8aa3b, v55
	v_exp_f32_e32 v55, v55
	v_cndmask_b32_e64 v63, v51, v59, s[8:9]
	v_readlane_b32 s8, v254, 29
	v_readlane_b32 s9, v254, 30
	s_nop 1
	v_cndmask_b32_e64 v63, v63, v55, s[8:9]
	v_add_f32_e32 v55, v55, v59
	v_add_f32_e32 v51, v51, v55
	v_div_scale_f32 v55, s[8:9], v51, v51, v63
	v_rcp_f32_e32 v59, v55
	v_mad_u64_u32 v[30:31], s[8:9], v78, 48, v[30:31]
	v_mov_b32_e32 v76, v31
	v_fma_f32 v67, -v55, v59, 1.0
	v_fmac_f32_e32 v59, v67, v59
	v_div_scale_f32 v67, vcc, v63, v51, v63
	v_mul_f32_e32 v71, v67, v59
	v_fma_f32 v74, -v55, v71, v67
	v_fmac_f32_e32 v71, v74, v59
	v_fma_f32 v55, -v55, v71, v67
	v_mad_u64_u32 v[76:77], s[8:9], v79, 48, v[76:77]
	v_div_fmas_f32 v55, v55, v59, v71
	v_mov_b32_e32 v31, v76
	v_div_fixup_f32 v74, v55, v51, v63
	global_load_dword v51, v[30:31], off
	global_load_dword v55, v[30:31], off offset:16
	global_load_dword v59, v[30:31], off offset:32
	v_mad_u64_u32 v[76:77], s[8:9], v78, s3, v[28:29]
	v_mov_b32_e32 v28, v77
	v_mad_u64_u32 v[28:29], s[8:9], v79, s3, v[28:29]
	v_readlane_b32 s8, v254, 41
	v_readlane_b32 s9, v254, 42
	v_mov_b32_e32 v77, v28
	global_load_dwordx4 v[28:31], v[76:77], off
	s_waitcnt vmcnt(1)
	v_max3_f32 v63, v51, v55, v59
	v_sub_f32_e32 v55, v55, v63
	v_sub_f32_e32 v59, v59, v63
	v_mul_f32_e32 v55, 0x3fb8aa3b, v55
	v_mul_f32_e32 v59, 0x3fb8aa3b, v59
	v_sub_f32_e32 v51, v51, v63
	v_exp_f32_e32 v55, v55
	v_exp_f32_e32 v59, v59
	v_mul_f32_e32 v51, 0x3fb8aa3b, v51
	v_exp_f32_e32 v51, v51
	v_cndmask_b32_e64 v63, v59, v55, s[8:9]
	v_readlane_b32 s8, v254, 33
	v_readlane_b32 s9, v254, 34
	s_nop 1
	v_cndmask_b32_e64 v63, v63, v51, s[8:9]
	v_add_f32_e32 v51, v51, v55
	v_add_f32_e32 v51, v59, v51
	v_div_scale_f32 v55, s[8:9], v51, v51, v63
	v_rcp_f32_e32 v59, v55
	s_nop 0
	v_fma_f32 v67, -v55, v59, 1.0
	v_fmac_f32_e32 v59, v67, v59
	v_div_scale_f32 v67, vcc, v63, v51, v63
	v_mul_f32_e32 v71, v67, v59
	v_fma_f32 v75, -v55, v71, v67
	v_fmac_f32_e32 v71, v75, v59
	v_fma_f32 v55, -v55, v71, v67
	v_div_fmas_f32 v55, v55, v59, v71
	v_div_fixup_f32 v78, v55, v51, v63
	v_or_b32_e32 v51, s44, v122
	v_mad_u64_u32 v[34:35], s[8:9], v51, 48, v[34:35]
	v_add_u32_e32 v35, s0, v35
	global_load_dword v55, v[34:35], off
	global_load_dword v59, v[34:35], off offset:16
	global_load_dword v63, v[34:35], off offset:32
	v_mad_u64_u32 v[80:81], s[8:9], v51, s3, v[32:33]
	v_readlane_b32 s8, v254, 49
	v_readlane_b32 s9, v254, 50
	v_add_u32_e32 v81, s1, v81
	global_load_dwordx4 v[32:35], v[80:81], off
	s_waitcnt vmcnt(1)
	v_max3_f32 v51, v55, v59, v63
	v_sub_f32_e32 v55, v55, v51
	v_sub_f32_e32 v59, v59, v51
	v_sub_f32_e32 v51, v63, v51
	v_mul_f32_e32 v59, 0x3fb8aa3b, v59
	v_mul_f32_e32 v51, 0x3fb8aa3b, v51
	v_exp_f32_e32 v59, v59
	v_exp_f32_e32 v51, v51
	v_mul_f32_e32 v55, 0x3fb8aa3b, v55
	v_exp_f32_e32 v55, v55
	v_cndmask_b32_e64 v63, v51, v59, s[8:9]
	v_readlane_b32 s8, v254, 43
	v_readlane_b32 s9, v254, 44
	s_nop 1
	v_cndmask_b32_e64 v63, v63, v55, s[8:9]
	v_add_f32_e32 v55, v55, v59
	v_add_f32_e32 v51, v51, v55
	v_div_scale_f32 v55, s[8:9], v51, v51, v63
	v_rcp_f32_e32 v59, v55
	s_nop 0
	v_fma_f32 v67, -v55, v59, 1.0
	v_fmac_f32_e32 v59, v67, v59
	v_div_scale_f32 v67, vcc, v63, v51, v63
	v_mul_f32_e32 v71, v67, v59
	v_fma_f32 v75, -v55, v71, v67
	v_fmac_f32_e32 v71, v75, v59
	v_fma_f32 v55, -v55, v71, v67
	v_div_fmas_f32 v55, v55, v59, v71
	v_div_fixup_f32 v82, v55, v51, v63
	v_or_b32_e32 v51, s44, v124
	v_mad_u64_u32 v[38:39], s[8:9], v51, 48, v[38:39]
	v_add_u32_e32 v39, s0, v39
	global_load_dword v55, v[38:39], off
	global_load_dword v59, v[38:39], off offset:16
	global_load_dword v63, v[38:39], off offset:32
	v_mad_u64_u32 v[84:85], s[8:9], v51, s3, v[36:37]
	v_readlane_b32 s8, v254, 37
	v_readlane_b32 s9, v254, 38
	v_add_u32_e32 v85, s1, v85
	global_load_dwordx4 v[36:39], v[84:85], off
	s_waitcnt vmcnt(1)
	v_max3_f32 v51, v55, v59, v63
	v_sub_f32_e32 v55, v55, v51
	v_sub_f32_e32 v59, v59, v51
	v_sub_f32_e32 v51, v63, v51
	v_mul_f32_e32 v59, 0x3fb8aa3b, v59
	v_mul_f32_e32 v51, 0x3fb8aa3b, v51
	v_exp_f32_e32 v59, v59
	v_exp_f32_e32 v51, v51
	v_mul_f32_e32 v55, 0x3fb8aa3b, v55
	v_exp_f32_e32 v55, v55
	v_cndmask_b32_e64 v63, v51, v59, s[8:9]
	v_readlane_b32 s8, v254, 35
	v_readlane_b32 s9, v254, 36
	s_nop 1
	v_cndmask_b32_e64 v63, v63, v55, s[8:9]
	v_add_f32_e32 v55, v55, v59
	v_add_f32_e32 v51, v51, v55
	v_div_scale_f32 v55, s[8:9], v51, v51, v63
	v_rcp_f32_e32 v59, v55
	s_nop 0
	v_fma_f32 v67, -v55, v59, 1.0
	v_fmac_f32_e32 v59, v67, v59
	v_div_scale_f32 v67, vcc, v63, v51, v63
	v_mul_f32_e32 v71, v67, v59
	v_fma_f32 v75, -v55, v71, v67
	v_fmac_f32_e32 v71, v75, v59
	v_fma_f32 v55, -v55, v71, v67
	v_div_fmas_f32 v55, v55, v59, v71
	v_div_fixup_f32 v86, v55, v51, v63
	v_or_b32_e32 v51, s44, v126
	v_mad_u64_u32 v[42:43], s[8:9], v51, 48, v[42:43]
	v_add_u32_e32 v43, s0, v43
	global_load_dword v55, v[42:43], off
	global_load_dword v59, v[42:43], off offset:16
	global_load_dword v63, v[42:43], off offset:32
	v_mad_u64_u32 v[88:89], s[8:9], v51, s3, v[40:41]
	v_add_u32_e32 v89, s1, v89
	v_readlane_b32 s0, v254, 53
	v_readlane_b32 s1, v254, 54
	global_load_dwordx4 v[40:43], v[88:89], off
	s_waitcnt vmcnt(1)
	v_max3_f32 v51, v55, v59, v63
	v_sub_f32_e32 v55, v55, v51
	v_sub_f32_e32 v59, v59, v51
	v_sub_f32_e32 v51, v63, v51
	v_mul_f32_e32 v59, 0x3fb8aa3b, v59
	v_mul_f32_e32 v51, 0x3fb8aa3b, v51
	v_exp_f32_e32 v59, v59
	v_exp_f32_e32 v51, v51
	v_mul_f32_e32 v55, 0x3fb8aa3b, v55
	v_exp_f32_e32 v55, v55
	v_cndmask_b32_e64 v63, v51, v59, s[0:1]
	v_readlane_b32 s0, v254, 39
	v_readlane_b32 s1, v254, 40
	s_nop 1
	v_cndmask_b32_e64 v63, v63, v55, s[0:1]
	v_add_f32_e32 v55, v55, v59
	v_add_f32_e32 v51, v51, v55
	v_div_scale_f32 v55, s[0:1], v51, v51, v63
	v_rcp_f32_e32 v59, v55
	v_mad_u64_u32 v[46:47], s[0:1], v94, 48, v[46:47]
	v_mov_b32_e32 v92, v47
	v_fma_f32 v67, -v55, v59, 1.0
	v_fmac_f32_e32 v59, v67, v59
	v_div_scale_f32 v67, vcc, v63, v51, v63
	v_mul_f32_e32 v71, v67, v59
	v_fma_f32 v75, -v55, v71, v67
	v_fmac_f32_e32 v71, v75, v59
	v_fma_f32 v55, -v55, v71, v67
	v_mad_u64_u32 v[92:93], s[0:1], v95, 48, v[92:93]
	v_div_fmas_f32 v55, v55, v59, v71
	v_mov_b32_e32 v47, v92
	v_div_fixup_f32 v90, v55, v51, v63
	global_load_dword v51, v[46:47], off
	global_load_dword v55, v[46:47], off offset:16
	global_load_dword v59, v[46:47], off offset:32
	v_mad_u64_u32 v[92:93], s[0:1], v94, s3, v[44:45]
	v_mov_b32_e32 v44, v93
	v_mad_u64_u32 v[44:45], s[0:1], v95, s3, v[44:45]
	v_mov_b32_e32 v93, v44
	global_load_dwordx4 v[44:47], v[92:93], off
	v_readlane_b32 s0, v254, 57
	v_readlane_b32 s1, v254, 58
	s_waitcnt vmcnt(1)
	v_max3_f32 v63, v51, v55, v59
	v_sub_f32_e32 v55, v55, v63
	v_sub_f32_e32 v59, v59, v63
	v_mul_f32_e32 v55, 0x3fb8aa3b, v55
	v_mul_f32_e32 v59, 0x3fb8aa3b, v59
	v_sub_f32_e32 v51, v51, v63
	v_exp_f32_e32 v55, v55
	v_exp_f32_e32 v59, v59
	v_mul_f32_e32 v51, 0x3fb8aa3b, v51
	v_exp_f32_e32 v51, v51
	v_cndmask_b32_e64 v63, v59, v55, s[0:1]
	v_readlane_b32 s0, v254, 55
	v_readlane_b32 s1, v254, 56
	s_nop 1
	v_cndmask_b32_e64 v63, v63, v51, s[0:1]
	v_add_f32_e32 v51, v51, v55
	v_add_f32_e32 v51, v59, v51
	v_div_scale_f32 v55, s[0:1], v51, v51, v63
	v_rcp_f32_e32 v59, v55
	v_pk_mul_f32 v[96:97], v[50:51], v[96:97] op_sel_hi:[0,1]
	v_cvt_pk_bf16_f32 v0, v96, v97
	v_lshlrev_b32_e32 v96, 16, v1
	v_fma_f32 v67, -v55, v59, 1.0
	v_fmac_f32_e32 v59, v67, v59
	v_div_scale_f32 v67, vcc, v63, v51, v63
	v_mul_f32_e32 v71, v67, v59
	v_and_b32_e32 v97, 0xffff0000, v1
	v_fma_f32 v75, -v55, v71, v67
	v_pk_mul_f32 v[96:97], v[50:51], v[96:97] op_sel_hi:[0,1]
	v_fmac_f32_e32 v71, v75, v59
	v_cvt_pk_bf16_f32 v1, v96, v97
	v_lshlrev_b32_e32 v96, 16, v2
	v_and_b32_e32 v97, 0xffff0000, v2
	v_fma_f32 v55, -v55, v71, v67
	v_pk_mul_f32 v[96:97], v[50:51], v[96:97] op_sel_hi:[0,1]
	v_div_fmas_f32 v55, v55, v59, v71
	v_cvt_pk_bf16_f32 v2, v96, v97
	v_lshlrev_b32_e32 v96, 16, v3
	v_and_b32_e32 v97, 0xffff0000, v3
	v_div_fixup_f32 v94, v55, v51, v63
	v_pk_mul_f32 v[50:51], v[50:51], v[96:97] op_sel_hi:[0,1]
	v_cvt_pk_bf16_f32 v3, v50, v51
	global_store_dwordx4 v[48:49], v[0:3], off
	v_readlane_b32 s0, v255, 1
	v_readlane_b32 s1, v255, 2
	v_lshlrev_b32_e32 v0, 16, v4
	v_and_b32_e32 v1, 0xffff0000, v4
	v_lshlrev_b32_e32 v2, 16, v5
	v_and_b32_e32 v3, 0xffff0000, v5
	v_pk_mul_f32 v[0:1], v[54:55], v[0:1] op_sel_hi:[0,1]
	v_pk_mul_f32 v[2:3], v[54:55], v[2:3] op_sel_hi:[0,1]
	v_cvt_pk_bf16_f32 v0, v0, v1
	v_cvt_pk_bf16_f32 v1, v2, v3
	v_lshlrev_b32_e32 v2, 16, v6
	v_and_b32_e32 v3, 0xffff0000, v6
	v_lshlrev_b32_e32 v4, 16, v7
	v_and_b32_e32 v5, 0xffff0000, v7
	v_pk_mul_f32 v[2:3], v[54:55], v[2:3] op_sel_hi:[0,1]
	v_pk_mul_f32 v[4:5], v[54:55], v[4:5] op_sel_hi:[0,1]
	v_cvt_pk_bf16_f32 v2, v2, v3
	v_cvt_pk_bf16_f32 v3, v4, v5
	global_store_dwordx4 v[52:53], v[0:3], off
	v_lshlrev_b32_e32 v4, 16, v11
	v_and_b32_e32 v5, 0xffff0000, v11
	v_lshlrev_b32_e32 v0, 16, v8
	v_and_b32_e32 v1, 0xffff0000, v8
	v_lshlrev_b32_e32 v2, 16, v9
	v_and_b32_e32 v3, 0xffff0000, v9
	v_pk_mul_f32 v[0:1], v[58:59], v[0:1] op_sel_hi:[0,1]
	v_pk_mul_f32 v[2:3], v[58:59], v[2:3] op_sel_hi:[0,1]
	v_cvt_pk_bf16_f32 v0, v0, v1
	v_cvt_pk_bf16_f32 v1, v2, v3
	v_lshlrev_b32_e32 v2, 16, v10
	v_and_b32_e32 v3, 0xffff0000, v10
	v_pk_mul_f32 v[2:3], v[58:59], v[2:3] op_sel_hi:[0,1]
	v_pk_mul_f32 v[4:5], v[58:59], v[4:5] op_sel_hi:[0,1]
	v_cvt_pk_bf16_f32 v2, v2, v3
	v_cvt_pk_bf16_f32 v3, v4, v5
	global_store_dwordx4 v[56:57], v[0:3], off
	v_lshlrev_b32_e32 v4, 16, v15
	v_and_b32_e32 v5, 0xffff0000, v15
	v_lshlrev_b32_e32 v0, 16, v12
	v_and_b32_e32 v1, 0xffff0000, v12
	v_lshlrev_b32_e32 v2, 16, v13
	v_and_b32_e32 v3, 0xffff0000, v13
	v_pk_mul_f32 v[0:1], v[62:63], v[0:1] op_sel_hi:[0,1]
	v_pk_mul_f32 v[2:3], v[62:63], v[2:3] op_sel_hi:[0,1]
	v_cvt_pk_bf16_f32 v0, v0, v1
	v_cvt_pk_bf16_f32 v1, v2, v3
	v_lshlrev_b32_e32 v2, 16, v14
	v_and_b32_e32 v3, 0xffff0000, v14
	v_pk_mul_f32 v[2:3], v[62:63], v[2:3] op_sel_hi:[0,1]
	v_pk_mul_f32 v[4:5], v[62:63], v[4:5] op_sel_hi:[0,1]
	v_cvt_pk_bf16_f32 v2, v2, v3
	v_cvt_pk_bf16_f32 v3, v4, v5
	global_store_dwordx4 v[60:61], v[0:3], off
	v_lshlrev_b32_e32 v4, 16, v19
	v_and_b32_e32 v5, 0xffff0000, v19
	v_lshlrev_b32_e32 v0, 16, v16
	v_and_b32_e32 v1, 0xffff0000, v16
	v_lshlrev_b32_e32 v2, 16, v17
	v_and_b32_e32 v3, 0xffff0000, v17
	v_pk_mul_f32 v[0:1], v[66:67], v[0:1] op_sel_hi:[0,1]
	v_pk_mul_f32 v[2:3], v[66:67], v[2:3] op_sel_hi:[0,1]
	v_cvt_pk_bf16_f32 v0, v0, v1
	v_cvt_pk_bf16_f32 v1, v2, v3
	v_lshlrev_b32_e32 v2, 16, v18
	v_and_b32_e32 v3, 0xffff0000, v18
	v_pk_mul_f32 v[2:3], v[66:67], v[2:3] op_sel_hi:[0,1]
	v_pk_mul_f32 v[4:5], v[66:67], v[4:5] op_sel_hi:[0,1]
	v_cvt_pk_bf16_f32 v2, v2, v3
	v_cvt_pk_bf16_f32 v3, v4, v5
	global_store_dwordx4 v[64:65], v[0:3], off
	v_lshlrev_b32_e32 v4, 16, v23
	v_and_b32_e32 v5, 0xffff0000, v23
	v_lshlrev_b32_e32 v0, 16, v20
	v_and_b32_e32 v1, 0xffff0000, v20
	v_lshlrev_b32_e32 v2, 16, v21
	v_and_b32_e32 v3, 0xffff0000, v21
	v_pk_mul_f32 v[0:1], v[70:71], v[0:1] op_sel_hi:[0,1]
	v_pk_mul_f32 v[2:3], v[70:71], v[2:3] op_sel_hi:[0,1]
	v_cvt_pk_bf16_f32 v0, v0, v1
	v_cvt_pk_bf16_f32 v1, v2, v3
	v_lshlrev_b32_e32 v2, 16, v22
	v_and_b32_e32 v3, 0xffff0000, v22
	v_pk_mul_f32 v[2:3], v[70:71], v[2:3] op_sel_hi:[0,1]
	v_pk_mul_f32 v[4:5], v[70:71], v[4:5] op_sel_hi:[0,1]
	v_cvt_pk_bf16_f32 v2, v2, v3
	v_cvt_pk_bf16_f32 v3, v4, v5
	global_store_dwordx4 v[68:69], v[0:3], off
	v_lshlrev_b32_e32 v4, 16, v27
	v_and_b32_e32 v5, 0xffff0000, v27
	v_lshlrev_b32_e32 v0, 16, v24
	v_and_b32_e32 v1, 0xffff0000, v24
	v_lshlrev_b32_e32 v2, 16, v25
	v_and_b32_e32 v3, 0xffff0000, v25
	v_pk_mul_f32 v[0:1], v[74:75], v[0:1] op_sel_hi:[0,1]
	v_pk_mul_f32 v[2:3], v[74:75], v[2:3] op_sel_hi:[0,1]
	v_cvt_pk_bf16_f32 v0, v0, v1
	v_cvt_pk_bf16_f32 v1, v2, v3
	v_lshlrev_b32_e32 v2, 16, v26
	v_and_b32_e32 v3, 0xffff0000, v26
	v_pk_mul_f32 v[2:3], v[74:75], v[2:3] op_sel_hi:[0,1]
	v_pk_mul_f32 v[4:5], v[74:75], v[4:5] op_sel_hi:[0,1]
	v_cvt_pk_bf16_f32 v2, v2, v3
	v_cvt_pk_bf16_f32 v3, v4, v5
	global_store_dwordx4 v[72:73], v[0:3], off
	v_lshlrev_b32_e32 v4, 16, v31
	v_and_b32_e32 v5, 0xffff0000, v31
	v_lshlrev_b32_e32 v0, 16, v28
	v_and_b32_e32 v1, 0xffff0000, v28
	v_lshlrev_b32_e32 v2, 16, v29
	v_and_b32_e32 v3, 0xffff0000, v29
	v_pk_mul_f32 v[0:1], v[78:79], v[0:1] op_sel_hi:[0,1]
	v_pk_mul_f32 v[2:3], v[78:79], v[2:3] op_sel_hi:[0,1]
	v_cvt_pk_bf16_f32 v0, v0, v1
	v_cvt_pk_bf16_f32 v1, v2, v3
	v_lshlrev_b32_e32 v2, 16, v30
	v_and_b32_e32 v3, 0xffff0000, v30
	v_pk_mul_f32 v[2:3], v[78:79], v[2:3] op_sel_hi:[0,1]
	v_pk_mul_f32 v[4:5], v[78:79], v[4:5] op_sel_hi:[0,1]
	v_cvt_pk_bf16_f32 v2, v2, v3
	v_cvt_pk_bf16_f32 v3, v4, v5
	global_store_dwordx4 v[76:77], v[0:3], off
	v_lshlrev_b32_e32 v4, 16, v35
	v_and_b32_e32 v5, 0xffff0000, v35
	v_lshlrev_b32_e32 v0, 16, v32
	v_and_b32_e32 v1, 0xffff0000, v32
	v_lshlrev_b32_e32 v2, 16, v33
	v_and_b32_e32 v3, 0xffff0000, v33
	v_pk_mul_f32 v[0:1], v[82:83], v[0:1] op_sel_hi:[0,1]
	v_pk_mul_f32 v[2:3], v[82:83], v[2:3] op_sel_hi:[0,1]
	v_cvt_pk_bf16_f32 v0, v0, v1
	v_cvt_pk_bf16_f32 v1, v2, v3
	v_lshlrev_b32_e32 v2, 16, v34
	v_and_b32_e32 v3, 0xffff0000, v34
	v_pk_mul_f32 v[2:3], v[82:83], v[2:3] op_sel_hi:[0,1]
	v_pk_mul_f32 v[4:5], v[82:83], v[4:5] op_sel_hi:[0,1]
	v_cvt_pk_bf16_f32 v2, v2, v3
	v_cvt_pk_bf16_f32 v3, v4, v5
	global_store_dwordx4 v[80:81], v[0:3], off
	v_lshlrev_b32_e32 v4, 16, v39
	v_and_b32_e32 v5, 0xffff0000, v39
	v_lshlrev_b32_e32 v0, 16, v36
	v_and_b32_e32 v1, 0xffff0000, v36
	v_lshlrev_b32_e32 v2, 16, v37
	v_and_b32_e32 v3, 0xffff0000, v37
	v_pk_mul_f32 v[0:1], v[86:87], v[0:1] op_sel_hi:[0,1]
	v_pk_mul_f32 v[2:3], v[86:87], v[2:3] op_sel_hi:[0,1]
	v_cvt_pk_bf16_f32 v0, v0, v1
	v_cvt_pk_bf16_f32 v1, v2, v3
	v_lshlrev_b32_e32 v2, 16, v38
	v_and_b32_e32 v3, 0xffff0000, v38
	v_pk_mul_f32 v[2:3], v[86:87], v[2:3] op_sel_hi:[0,1]
	v_pk_mul_f32 v[4:5], v[86:87], v[4:5] op_sel_hi:[0,1]
	v_cvt_pk_bf16_f32 v2, v2, v3
	v_cvt_pk_bf16_f32 v3, v4, v5
	global_store_dwordx4 v[84:85], v[0:3], off
	v_lshlrev_b32_e32 v4, 16, v43
	v_and_b32_e32 v5, 0xffff0000, v43
	v_lshlrev_b32_e32 v0, 16, v40
	v_and_b32_e32 v1, 0xffff0000, v40
	v_lshlrev_b32_e32 v2, 16, v41
	v_and_b32_e32 v3, 0xffff0000, v41
	v_pk_mul_f32 v[0:1], v[90:91], v[0:1] op_sel_hi:[0,1]
	v_pk_mul_f32 v[2:3], v[90:91], v[2:3] op_sel_hi:[0,1]
	v_cvt_pk_bf16_f32 v0, v0, v1
	v_cvt_pk_bf16_f32 v1, v2, v3
	v_lshlrev_b32_e32 v2, 16, v42
	v_and_b32_e32 v3, 0xffff0000, v42
	v_pk_mul_f32 v[2:3], v[90:91], v[2:3] op_sel_hi:[0,1]
	v_pk_mul_f32 v[4:5], v[90:91], v[4:5] op_sel_hi:[0,1]
	v_cvt_pk_bf16_f32 v2, v2, v3
	v_cvt_pk_bf16_f32 v3, v4, v5
	global_store_dwordx4 v[88:89], v[0:3], off
	s_waitcnt vmcnt(11)
	v_lshlrev_b32_e32 v4, 16, v47
	v_and_b32_e32 v5, 0xffff0000, v47
	v_lshlrev_b32_e32 v0, 16, v44
	v_and_b32_e32 v1, 0xffff0000, v44
	v_lshlrev_b32_e32 v2, 16, v45
	v_and_b32_e32 v3, 0xffff0000, v45
	v_pk_mul_f32 v[0:1], v[94:95], v[0:1] op_sel_hi:[0,1]
	v_pk_mul_f32 v[2:3], v[94:95], v[2:3] op_sel_hi:[0,1]
	v_cvt_pk_bf16_f32 v0, v0, v1
	v_cvt_pk_bf16_f32 v1, v2, v3
	v_lshlrev_b32_e32 v2, 16, v46
	v_and_b32_e32 v3, 0xffff0000, v46
	v_pk_mul_f32 v[2:3], v[94:95], v[2:3] op_sel_hi:[0,1]
	v_pk_mul_f32 v[4:5], v[94:95], v[4:5] op_sel_hi:[0,1]
	s_xor_b64 s[14:15], s[14:15], s[0:1]
	v_cvt_pk_bf16_f32 v2, v2, v3
	v_cvt_pk_bf16_f32 v3, v4, v5
	s_cmpk_lt_i32 s49, 0x108
	global_store_dwordx4 v[92:93], v[0:3], off
	s_cbranch_scc0 .LBB0_883
